# attention loop-edge edits: pointer increments and lrun add moved off the path between the last PV MFMA and the barrier; redundant canonicalising VALU removed
# baseline (speedup 1.0000x reference)
; __device__ __forceinline__ void unit(const Ctx& F, int b, int h, int qb, const bf16_t* Q, const bf16_t* Kg, const bf16_t* VT, bf16_t* O, float lam) {
;     ...
;     ATT_DMA(0, 0); ATT_DMA(1, BUF);
; #pragma nounroll
;     for (int j = 0; j < NT; ++j) {
;         if (j + 1 < NT) asm volatile("s_waitcnt vmcnt(4) lgkmcnt(0)" ::: "memory"); else asm volatile("s_waitcnt vmcnt(0) lgkmcnt(0)" ::: "memory");
;         __builtin_amdgcn_s_barrier(); asm volatile("" ::: "memory");
;         if (j + 2 < NT) ATT_DMA(j + 2, ((j + 2) % 3) * BUF);
;         if (j <= cq) { const int bo = (j % 3) * BUF; ATT_S(bo); ATT_PV(bo); }
;     }
.LBB0_235:
	v_sub_f32_e32 v80, v80, v145
	v_exp_f32_e32 v80, v80
	v_sub_f32_e32 v81, v81, v145
	v_exp_f32_e32 v81, v81
	v_sub_f32_e32 v82, v82, v145
	v_exp_f32_e32 v82, v82
	v_sub_f32_e32 v83, v83, v145
	v_exp_f32_e32 v83, v83
	v_sub_f32_e32 v84, v84, v145
	v_exp_f32_e32 v84, v84
	v_sub_f32_e32 v85, v85, v145
	v_add_f32_e32 v188, v81, v80
	v_exp_f32_e32 v85, v85
	v_sub_f32_e32 v86, v86, v145
	v_add_f32_e32 v188, v82, v188
	v_exp_f32_e32 v86, v86
	v_sub_f32_e32 v87, v87, v145
	v_add_f32_e32 v188, v83, v188
	v_exp_f32_e32 v87, v87
	v_sub_f32_e32 v88, v88, v145
	v_add_f32_e32 v188, v84, v188
	v_exp_f32_e32 v88, v88
	v_sub_f32_e32 v89, v89, v145
	v_add_f32_e32 v188, v85, v188
	v_exp_f32_e32 v89, v89
	v_sub_f32_e32 v90, v90, v145
	v_add_f32_e32 v188, v86, v188
	v_exp_f32_e32 v90, v90
	v_sub_f32_e32 v91, v91, v145
	v_add_f32_e32 v188, v87, v188
	v_exp_f32_e32 v91, v91
	v_sub_f32_e32 v92, v92, v145
	v_add_f32_e32 v188, v88, v188
	v_exp_f32_e32 v92, v92
	v_sub_f32_e32 v93, v93, v145
	v_add_f32_e32 v188, v89, v188
	v_exp_f32_e32 v93, v93
	v_sub_f32_e32 v94, v94, v145
	v_add_f32_e32 v188, v90, v188
	v_exp_f32_e32 v94, v94
	v_sub_f32_e32 v95, v95, v145
	v_add_f32_e32 v188, v91, v188
	v_exp_f32_e32 v95, v95
	v_sub_f32_e32 v64, v64, v145
	v_add_f32_e32 v188, v92, v188
	v_exp_f32_e32 v189, v64
	v_sub_f32_e32 v64, v65, v145
	v_add_f32_e32 v188, v93, v188
	v_exp_f32_e32 v190, v64
	v_sub_f32_e32 v64, v66, v145
	v_add_f32_e32 v188, v94, v188
	v_exp_f32_e32 v191, v64
	v_sub_f32_e32 v64, v67, v145
	v_add_f32_e32 v188, v95, v188
	v_exp_f32_e32 v192, v64
	v_sub_f32_e32 v65, v68, v145
	v_add_f32_e32 v64, v189, v188
	v_exp_f32_e32 v188, v65
	v_sub_f32_e32 v65, v69, v145
	v_add_f32_e32 v64, v190, v64
	v_exp_f32_e32 v193, v65
	v_sub_f32_e32 v65, v70, v145
	v_add_f32_e32 v64, v191, v64
	v_exp_f32_e32 v194, v65
	v_sub_f32_e32 v65, v71, v145
	v_add_f32_e32 v64, v192, v64
	v_exp_f32_e32 v195, v65
	v_sub_f32_e32 v65, v72, v145
	v_add_f32_e32 v64, v188, v64
	v_exp_f32_e32 v196, v65
	v_sub_f32_e32 v65, v73, v145
	v_add_f32_e32 v64, v193, v64
	v_exp_f32_e32 v197, v65
	v_sub_f32_e32 v65, v74, v145
	v_add_f32_e32 v64, v194, v64
	v_exp_f32_e32 v198, v65
	v_sub_f32_e32 v65, v75, v145
	v_add_f32_e32 v64, v195, v64
	v_exp_f32_e32 v199, v65
	v_sub_f32_e32 v65, v76, v145
	v_add_f32_e32 v64, v196, v64
	v_exp_f32_e32 v200, v65
	v_sub_f32_e32 v65, v77, v145
	v_add_f32_e32 v64, v197, v64
	v_exp_f32_e32 v201, v65
	v_sub_f32_e32 v65, v78, v145
	v_add_f32_e32 v64, v198, v64
	v_exp_f32_e32 v202, v65
	v_sub_f32_e32 v65, v79, v145
	v_add_f32_e32 v64, v199, v64
	v_exp_f32_e32 v79, v65
	v_add_f32_e32 v64, v200, v64
	v_add_f32_e32 v64, v201, v64
	v_subrev_u32_e32 v151, s26, v176
	v_subrev_u32_e32 v187, s26, v174
	v_add_f32_e32 v64, v202, v64
	v_add_u32_e32 v204, s54, v181
	v_add_f32_e32 v212, v79, v64
	v_cvt_pk_bf16_f32 v64, v80, v81
	v_cvt_pk_bf16_f32 v65, v82, v83
	v_cvt_pk_bf16_f32 v66, v84, v85
	v_cvt_pk_bf16_f32 v67, v86, v87
	v_cvt_pk_bf16_f32 v68, v88, v89
	v_cvt_pk_bf16_f32 v69, v90, v91
	v_cvt_pk_bf16_f32 v70, v92, v93
	v_add_u32_e32 v92, v204, v187
	v_add_u32_e32 v151, v204, v151
	v_cvt_pk_bf16_f32 v71, v94, v95
	v_cvt_pk_bf16_f32 v72, v189, v190
	v_cvt_pk_bf16_f32 v73, v191, v192
	v_cvt_pk_bf16_f32 v74, v188, v193
	v_cvt_pk_bf16_f32 v75, v194, v195
	v_cvt_pk_bf16_f32 v76, v196, v197
	v_cvt_pk_bf16_f32 v77, v198, v199
	v_cvt_pk_bf16_f32 v78, v200, v201
	v_cvt_pk_bf16_f32 v79, v202, v79
	ds_read_b128 v[80:83], v92 offset:16384
	ds_read_b128 v[84:87], v92 offset:20480
	ds_read_b128 v[88:91], v92 offset:24576
	ds_read_b128 v[92:95], v92 offset:28672
	ds_read_b128 v[188:191], v151 offset:16384
	ds_read_b128 v[192:195], v151 offset:20480
	ds_read_b128 v[196:199], v151 offset:24576
	ds_read_b128 v[200:203], v151 offset:28672
	v_subrev_u32_e32 v147, s26, v180
	v_subrev_u32_e32 v149, s26, v178
	v_add_u32_e32 v149, v204, v149
	v_add_u32_e32 v147, v204, v147
	ds_read_b128 v[208:211], v149 offset:16384
	ds_read_b128 v[214:217], v149 offset:20480
	ds_read_b128 v[230:233], v149 offset:24576
	ds_read_b128 v[234:237], v149 offset:28672
	ds_read_b128 v[238:241], v147 offset:16384
	ds_read_b128 v[242:245], v147 offset:20480
	ds_read_b128 v[246:249], v147 offset:24576
	ds_read_b128 v[204:207], v147 offset:28672
	v_add_f32_e32 v143, v143, v212
	v_lshl_add_u64 v[152:153], v[152:153], 0, s[18:19]
	v_lshl_add_u64 v[154:155], v[154:155], 0, s[38:39]
	v_lshl_add_u64 v[168:169], v[168:169], 0, s[38:39]
	v_lshl_add_u64 v[170:171], v[170:171], 0, s[18:19]
	s_setprio 1
	s_waitcnt lgkmcnt(0)
	v_mfma_f32_32x32x16_bf16 v[48:63], v[80:83], v[64:67], v[48:63]
	v_mfma_f32_32x32x16_bf16 v[48:63], v[188:191], v[68:71], v[48:63]
	v_mfma_f32_32x32x16_bf16 v[48:63], v[208:211], v[72:75], v[48:63]
	v_mfma_f32_32x32x16_bf16 v[48:63], v[238:241], v[76:79], v[48:63]
	v_mfma_f32_32x32x16_bf16 v[32:47], v[84:87], v[64:67], v[32:47]
	v_mfma_f32_32x32x16_bf16 v[32:47], v[192:195], v[68:71], v[32:47]
	v_mfma_f32_32x32x16_bf16 v[32:47], v[214:217], v[72:75], v[32:47]
	v_mfma_f32_32x32x16_bf16 v[32:47], v[242:245], v[76:79], v[32:47]
	v_mfma_f32_32x32x16_bf16 v[16:31], v[88:91], v[64:67], v[16:31]
	v_mfma_f32_32x32x16_bf16 v[16:31], v[196:199], v[68:71], v[16:31]
	v_mfma_f32_32x32x16_bf16 v[16:31], v[230:233], v[72:75], v[16:31]
	v_mfma_f32_32x32x16_bf16 v[16:31], v[246:249], v[76:79], v[16:31]
	v_mfma_f32_32x32x16_bf16 v[0:15], v[92:95], v[64:67], v[0:15]
	v_mfma_f32_32x32x16_bf16 v[0:15], v[200:203], v[68:71], v[0:15]
	v_mfma_f32_32x32x16_bf16 v[0:15], v[234:237], v[72:75], v[0:15]
	v_mfma_f32_32x32x16_bf16 v[0:15], v[204:207], v[76:79], v[0:15]
	s_setprio 0
.LBB0_236:
	s_add_i32 s54, s54, 0x8000
	s_add_i32 s45, s45, 1
	s_add_i32 s50, s50, 1
	s_add_i32 s55, s55, 1
	s_cmp_eq_u32 s53, s54
	s_cbranch_scc1 .LBB0_246

.LBB0_243:
	s_cmp_gt_i32 s26, s52
	s_cbranch_scc1 .LBB0_236
	s_mul_hi_u32 s26, s55, 0xaaaaaaab
	s_lshr_b32 s26, s26, 1
	s_mul_i32 s26, s26, 0x18000
	v_subrev_u32_e32 v72, s26, v179
	v_subrev_u32_e32 v73, s26, v177
	v_subrev_u32_e32 v74, s26, v175
	v_subrev_u32_e32 v64, s26, v173
	v_add_u32_e32 v75, s54, v182
	v_add_u32_e32 v68, v75, v64
	v_add_u32_e32 v74, v75, v74
	v_add_u32_e32 v73, v75, v73
	v_add_u32_e32 v72, v75, v72
	ds_read_b128 v[64:67], v68
	ds_read_b128 v[68:71], v68 offset:8192
	ds_read_b128 v[188:191], v74
	ds_read_b128 v[192:195], v74 offset:8192
	ds_read_b128 v[196:199], v73
	ds_read_b128 v[200:203], v73 offset:8192
	ds_read_b128 v[208:211], v72
	ds_read_b128 v[214:217], v72 offset:8192
	s_waitcnt lgkmcnt(0)
	s_setprio 1
	s_waitcnt lgkmcnt(0)
	v_mfma_f32_32x32x16_bf16 v[80:95], v[64:67], v[96:99], 0
	v_mfma_f32_32x32x16_bf16 v[80:95], v[188:191], v[100:103], v[80:95]
	v_mfma_f32_32x32x16_bf16 v[80:95], v[196:199], v[104:107], v[80:95]
	v_mfma_f32_32x32x16_bf16 v[80:95], v[208:211], v[108:111], v[80:95]
	v_mfma_f32_32x32x16_bf16 v[64:79], v[68:71], v[96:99], 0
	v_mfma_f32_32x32x16_bf16 v[64:79], v[192:195], v[100:103], v[64:79]
	v_mfma_f32_32x32x16_bf16 v[64:79], v[200:203], v[104:107], v[64:79]
	v_mfma_f32_32x32x16_bf16 v[64:79], v[214:217], v[108:111], v[64:79]
	s_setprio 0
	s_nop 10
	v_max3_f32 v147, v80, v81, v82
	v_max3_f32 v149, v64, v65, v66
	v_max3_f32 v147, v147, v83, v84
	v_max3_f32 v149, v149, v67, v68
	v_max3_f32 v147, v147, v85, v86
	v_max3_f32 v149, v149, v69, v70
	v_max3_f32 v147, v147, v87, v88
	v_max3_f32 v149, v149, v71, v72
	v_max3_f32 v147, v147, v89, v90
	v_max3_f32 v149, v149, v73, v74
	v_max3_f32 v147, v147, v91, v92
	v_max3_f32 v149, v149, v75, v76
	v_max3_f32 v147, v147, v93, v94
	v_max3_f32 v149, v149, v77, v78
	v_max3_f32 v147, v147, v95, v79
	v_max_f32_e32 v147, v147, v149
	v_mov_b32_e32 v149, v147
	s_nop 1
	v_permlane32_swap_b32_e32 v147, v149
	v_max_f32_e32 v147, v147, v149
	v_cmp_gt_f32_e32 vcc, v147, v145
	s_cbranch_vccz .LBB0_235
	v_max_f32_e32 v147, v147, v147
	v_max_f32_e32 v149, v145, v145
	v_max_f32_e32 v147, v149, v147
	v_sub_f32_e32 v145, v145, v147
	v_exp_f32_e32 v188, v145
	v_mov_b32_e32 v145, v147
	v_pk_mul_f32 v[62:63], v[62:63], v[188:189] op_sel_hi:[1,0]
	v_pk_mul_f32 v[60:61], v[60:61], v[188:189] op_sel_hi:[1,0]
	v_pk_mul_f32 v[58:59], v[58:59], v[188:189] op_sel_hi:[1,0]
	v_pk_mul_f32 v[56:57], v[56:57], v[188:189] op_sel_hi:[1,0]
	v_pk_mul_f32 v[54:55], v[54:55], v[188:189] op_sel_hi:[1,0]
	v_pk_mul_f32 v[52:53], v[52:53], v[188:189] op_sel_hi:[1,0]
	v_pk_mul_f32 v[50:51], v[50:51], v[188:189] op_sel_hi:[1,0]
	v_pk_mul_f32 v[48:49], v[48:49], v[188:189] op_sel_hi:[1,0]
	v_pk_mul_f32 v[46:47], v[46:47], v[188:189] op_sel_hi:[1,0]
	v_pk_mul_f32 v[44:45], v[44:45], v[188:189] op_sel_hi:[1,0]
	v_pk_mul_f32 v[42:43], v[42:43], v[188:189] op_sel_hi:[1,0]
	v_pk_mul_f32 v[40:41], v[40:41], v[188:189] op_sel_hi:[1,0]
	v_pk_mul_f32 v[38:39], v[38:39], v[188:189] op_sel_hi:[1,0]
	v_pk_mul_f32 v[36:37], v[36:37], v[188:189] op_sel_hi:[1,0]
	v_pk_mul_f32 v[34:35], v[34:35], v[188:189] op_sel_hi:[1,0]
	v_pk_mul_f32 v[32:33], v[32:33], v[188:189] op_sel_hi:[1,0]
	v_pk_mul_f32 v[30:31], v[30:31], v[188:189] op_sel_hi:[1,0]
	v_pk_mul_f32 v[28:29], v[28:29], v[188:189] op_sel_hi:[1,0]
	v_pk_mul_f32 v[26:27], v[26:27], v[188:189] op_sel_hi:[1,0]
	v_pk_mul_f32 v[24:25], v[24:25], v[188:189] op_sel_hi:[1,0]
	v_pk_mul_f32 v[22:23], v[22:23], v[188:189] op_sel_hi:[1,0]
	v_pk_mul_f32 v[20:21], v[20:21], v[188:189] op_sel_hi:[1,0]
	v_pk_mul_f32 v[18:19], v[18:19], v[188:189] op_sel_hi:[1,0]
	v_pk_mul_f32 v[16:17], v[16:17], v[188:189] op_sel_hi:[1,0]
	v_pk_mul_f32 v[14:15], v[14:15], v[188:189] op_sel_hi:[1,0]
	v_pk_mul_f32 v[12:13], v[12:13], v[188:189] op_sel_hi:[1,0]
	v_pk_mul_f32 v[10:11], v[10:11], v[188:189] op_sel_hi:[1,0]
	v_pk_mul_f32 v[8:9], v[8:9], v[188:189] op_sel_hi:[1,0]
	v_pk_mul_f32 v[6:7], v[6:7], v[188:189] op_sel_hi:[1,0]
	v_pk_mul_f32 v[4:5], v[4:5], v[188:189] op_sel_hi:[1,0]
	v_pk_mul_f32 v[2:3], v[2:3], v[188:189] op_sel_hi:[1,0]
	v_pk_mul_f32 v[0:1], v[0:1], v[188:189] op_sel_hi:[1,0]
	v_mul_f32_e32 v143, v143, v188
	s_branch .LBB0_235
